# attention early tile barrier: both per-tile barriers issued before the last PV MFMA pair (loop-head barrier rotated into the step1 PV tail, prologue gets its own)
# baseline (speedup 1.0000x reference)
.LBB0_182:
	s_lshr_b32 s6, s25, 1
	s_mul_i32 s6, s24, s6
	s_add_i32 s34, s17, s6
	s_lshl_b32 s6, s34, 4
	s_and_b32 s36, s6, 0xe00
	s_and_b32 s6, s34, 31
	s_ashr_i32 s8, s34, 8
	s_and_b32 s7, s25, 1
	s_xor_b32 s9, s6, 63
	v_mov_b32_e32 v4, v0
	s_cmp_eq_u32 s7, 0
	s_cselect_b32 s80, s6, s9
	v_readfirstlane_b32 s54, v4
	s_ashr_i32 s87, s54, 6
	s_ashr_i32 s9, s8, 31
	s_ashr_i32 s56, s54, 8
	s_and_b32 s57, s87, 3
	s_lshl_b32 s58, s80, 7
	s_lshl_b64 s[6:7], s[8:9], 13
	s_mul_i32 s88, s8, 0x14000000
	s_mul_hi_i32 s37, s8, 0x14000000
	s_add_u32 s8, s38, s88
	s_addc_u32 s9, s39, s37
	s_lshl_b32 s34, s34, 3
	s_and_b32 s55, s34, 0x700
	s_lshl_b32 s60, s55, 1
	s_add_u32 s8, s8, s60
	s_addc_u32 s9, s9, 0
	s_add_u32 s34, s8, 0x1000
	s_addc_u32 s35, s9, 0
	s_add_u32 s82, s8, 0x2000
	s_addc_u32 s83, s9, 0
	s_lshl_b32 s8, s57, 5
	s_or_b32 s59, s58, s8
	s_or_b32 s6, s59, s6
	s_mul_hi_u32 s9, s6, 0xa000
	s_mul_i32 s58, s7, 0xa000
	s_mul_i32 s8, s6, 0xa000
	s_add_i32 s9, s9, s58
	s_add_u32 s8, s38, s8
	s_addc_u32 s9, s39, s9
	s_add_u32 s58, s8, s60
	s_addc_u32 s60, s9, 0
	s_lshl_b32 s8, s56, 7
	s_ashr_i32 s9, s8, 31
	v_and_b32_e32 v14, 63, v4
	s_lshl_b64 s[8:9], s[8:9], 1
	s_add_u32 s8, s58, s8
	v_mov_b32_e32 v15, v14
	s_addc_u32 s9, s60, s9
	s_lshl_b32 s68, s87, 3
	v_ashrrev_i32_e32 v6, 4, v15
	v_and_b32_e32 v7, 15, v15
	v_add_u32_e32 v2, s68, v6
	s_and_b32 s58, s54, 0x3fffffc0
	s_waitcnt lgkmcnt(0)
	v_bitop3_b32 v3, v6, v7, 7 bitop3:0x6c
	v_mul_lo_u32 v2, v2, s45
	s_lshl_b32 s58, s58, 2
	v_lshl_or_b32 v2, v3, 3, v2
	s_lshl_b32 s61, s87, 11
	s_add_i32 s60, s58, 0
	s_lshl_b32 s58, s87, 1
	s_add_i32 s62, s61, 0
	v_ashrrev_i32_e32 v3, 31, v2
	v_lshl_add_u64 v[2:3], v[2:3], 1, s[34:35]
	s_mov_b32 m0, s62
	s_add_i32 s63, s62, 0x4000
	s_or_b32 s58, s58, 1
	global_load_lds_dwordx4 v[2:3], off
	v_lshl_add_u64 v[2:3], v[2:3], 0, s[12:13]
	s_mov_b32 m0, s63
	s_lshl_b32 s64, s58, 2
	global_load_lds_dwordx4 v[2:3], off
	v_add_u32_e32 v2, s64, v6
	v_bitop3_b32 v3, v2, v7, 7 bitop3:0x6c
	v_mul_lo_u32 v2, v2, s45
	v_lshl_or_b32 v2, v3, 3, v2
	s_lshl_b32 s65, s58, 10
	s_add_i32 s66, s65, 0
	v_ashrrev_i32_e32 v3, 31, v2
	s_andn2_b32 s68, s68, 31
	s_add_i32 s60, s60, 0x20400
	v_lshl_add_u64 v[2:3], v[2:3], 1, s[34:35]
	s_add_i32 s67, s66, 0x4000
	s_lshl_b32 s58, s87, 2
	s_mul_i32 s35, s68, 0xa000
	s_mul_hi_i32 s34, s68, 0xa000
	s_add_u32 s35, s82, s35
	s_mov_b32 m0, s66
	s_addc_u32 s69, s83, s34
	s_and_b32 s34, s54, 0x80
	global_load_lds_dwordx4 v[2:3], off
	v_lshl_add_u64 v[2:3], v[2:3], 0, s[12:13]
	s_mov_b32 m0, s67
	s_lshl_b32 s84, s34, 1
	global_load_lds_dwordx4 v[2:3], off
	v_lshrrev_b32_e32 v2, 2, v15
	s_add_u32 s34, s35, s84
	s_addc_u32 s35, s69, 0
	s_lshl_b32 s69, s87, 4
	v_bfe_u32 v2, v2, 2, 1
	v_bfe_u32 v16, v15, 2, 3
	s_and_b32 s69, s69, 16
	v_xor_b32_e32 v2, v2, v15
	v_or_b32_e32 v6, s69, v16
	v_and_b32_e32 v17, 0xffffffe0, v15
	v_lshlrev_b32_e32 v2, 3, v2
	v_and_b32_e32 v12, 24, v2
	v_mad_u32_u24 v2, v6, s45, v17
	s_lshl_b32 s70, s87, 12
	v_or_b32_e32 v2, v12, v2
	s_add_i32 s72, s70, 0
	v_ashrrev_i32_e32 v3, 31, v2
	s_add_i32 s71, s72, 0x8000
	v_and_b32_e32 v5, 31, v4
	v_lshl_add_u64 v[2:3], v[2:3], 1, s[34:35]
	s_mov_b32 m0, s71
	v_add_u32_e32 v18, 64, v17
	global_load_lds_dwordx4 v[2:3], off
	v_mul_u32_u24_e32 v2, 0x5000, v5
	v_mad_u32_u24 v13, v6, s45, v18
	v_lshlrev_b32_e32 v222, 1, v2
	v_lshl_add_u64 v[2:3], s[8:9], 0, v[222:223]
	v_lshrrev_b32_e32 v4, 1, v4
	v_or_b32_e32 v12, v12, v13
	s_or_b32 s8, s58, 2
	v_and_b32_e32 v222, 16, v4
	v_ashrrev_i32_e32 v13, 31, v12
	s_add_i32 s72, s72, 0x8400
	s_lshl_b32 s9, s8, 2
	v_lshl_add_u64 v[10:11], v[2:3], 0, v[222:223]
	v_lshl_add_u64 v[12:13], v[12:13], 1, s[34:35]
	s_mov_b32 m0, s72
	s_and_b32 s73, s9, 24
	global_load_dwordx4 v[2:5], v[10:11], off offset:192
	global_load_dwordx4 v[6:9], v[10:11], off offset:224
	s_lshl_b32 s74, s8, 10
	global_load_lds_dwordx4 v[12:13], off
	v_or_b32_e32 v12, s73, v16
	v_lshrrev_b32_e32 v13, 2, v12
	v_xor_b32_e32 v13, v13, v15
	v_lshlrev_b32_e32 v13, 3, v13
	v_mad_u32_u24 v12, v12, s45, v17
	v_and_or_b32 v12, v13, 24, v12
	s_add_i32 s75, s74, 0
	s_or_b32 s8, s58, 3
	v_ashrrev_i32_e32 v13, 31, v12
	s_add_i32 s75, s75, 0x8000
	s_lshl_b32 s9, s8, 2
	v_lshl_add_u64 v[12:13], v[12:13], 1, s[34:35]
	s_mov_b32 m0, s75
	s_and_b32 s76, s9, 24
	global_load_lds_dwordx4 v[12:13], off
	v_or_b32_e32 v12, s76, v16
	v_lshrrev_b32_e32 v13, 2, v12
	v_xor_b32_e32 v13, v13, v15
	v_lshlrev_b32_e32 v13, 3, v13
	v_mad_u32_u24 v12, v12, s45, v18
	s_lshl_b32 s77, s8, 10
	v_and_or_b32 v12, v13, 24, v12
	s_add_i32 s78, s77, 0
	v_ashrrev_i32_e32 v13, 31, v12
	s_add_i32 s78, s78, 0x8000
	v_lshl_add_u64 v[12:13], v[12:13], 1, s[34:35]
	s_mov_b32 m0, s78
	s_lshl_b32 s80, s80, 1
	global_load_lds_dwordx4 v[12:13], off
	global_load_dwordx4 v[34:37], v[10:11], off
	global_load_dwordx4 v[38:41], v[10:11], off offset:32
	global_load_dwordx4 v[42:45], v[10:11], off offset:64
	global_load_dwordx4 v[46:49], v[10:11], off offset:96
	global_load_dwordx4 v[50:53], v[10:11], off offset:128
	global_load_dwordx4 v[54:57], v[10:11], off offset:160
	s_add_i32 s81, s62, 0x22400
	s_add_u32 s82, s82, s84
	s_addc_u32 s83, s83, 0
	s_lshl_b32 s8, s56, 14
	s_add_i32 s84, s8, 0
	s_add_i32 s85, s84, 0x10000
	s_add_i32 s86, s59, 0x7fffffff
	s_or_b32 s8, s88, s36
	s_mul_i32 s87, s87, 0x28000
	s_add_u32 s8, s43, s8
	s_mov_b32 s79, 0
	v_lshl_add_u32 v10, v14, 4, s81
	s_addc_u32 s9, s44, s37
	s_add_i32 s88, s87, 0x14000
	v_mov_b32_e32 v186, 0xf149f2ca
	s_mov_b32 s89, 0
	v_mov_b32_e32 v187, 0
	s_waitcnt vmcnt(0)
	ds_write_b128 v10, v[2:5]
	ds_write_b128 v10, v[6:9] offset:1024
	v_mov_b32 v58, 0
	v_mov_b32 v59, 0
	v_mov_b32 v60, 0
	v_mov_b32 v61, 0
	v_mov_b32 v62, 0
	v_mov_b32 v63, 0
	v_mov_b32 v64, 0
	v_mov_b32 v65, 0
	v_mov_b32 v66, 0
	v_mov_b32 v67, 0
	v_mov_b32 v68, 0
	v_mov_b32 v69, 0
	v_mov_b32 v70, 0
	v_mov_b32 v71, 0
	v_mov_b32 v72, 0
	v_mov_b32 v73, 0
	v_mov_b32 v74, 0
	v_mov_b32 v75, 0
	v_mov_b32 v76, 0
	v_mov_b32 v77, 0
	v_mov_b32 v82, 0
	v_mov_b32 v83, 0
	v_mov_b32 v84, 0
	v_mov_b32 v85, 0
	v_mov_b32 v90, 0
	v_mov_b32 v91, 0
	v_mov_b32 v92, 0
	v_mov_b32 v93, 0
	v_mov_b32 v98, 0
	v_mov_b32 v99, 0
	v_mov_b32 v100, 0
	v_mov_b32 v101, 0
	v_mov_b32 v110, 0
	v_mov_b32 v111, 0
	v_mov_b32 v112, 0
	v_mov_b32 v113, 0
	v_mov_b32 v122, 0
	v_mov_b32 v123, 0
	v_mov_b32 v124, 0
	v_mov_b32 v125, 0
	v_mov_b32 v134, 0
	v_mov_b32 v135, 0
	v_mov_b32 v136, 0
	v_mov_b32 v137, 0
	v_mov_b32 v146, 0
	v_mov_b32 v147, 0
	v_mov_b32 v148, 0
	v_mov_b32 v149, 0
	v_mov_b32 v158, 0
	v_mov_b32 v159, 0
	v_mov_b32 v160, 0
	v_mov_b32 v161, 0
	v_mov_b32 v174, 0
	v_mov_b32 v175, 0
	v_mov_b32 v176, 0
	v_mov_b32 v177, 0
	v_mov_b32 v182, 0
	v_mov_b32 v183, 0
	v_mov_b32 v184, 0
	v_mov_b32 v185, 0
	v_mov_b32 v170, 0
	v_mov_b32 v171, 0
	v_mov_b32 v172, 0
	v_mov_b32 v173, 0
	v_mov_b32 v178, 0
	v_mov_b32 v179, 0
	v_mov_b32 v180, 0
	v_mov_b32 v181, 0
	v_mov_b32 v166, 0
	v_mov_b32 v167, 0
	v_mov_b32 v168, 0
	v_mov_b32 v169, 0
	v_mov_b32 v162, 0
	v_mov_b32 v163, 0
	v_mov_b32 v164, 0
	v_mov_b32 v165, 0
	v_mov_b32 v154, 0
	v_mov_b32 v155, 0
	v_mov_b32 v156, 0
	v_mov_b32 v157, 0
	v_mov_b32 v150, 0
	v_mov_b32 v151, 0
	v_mov_b32 v152, 0
	v_mov_b32 v153, 0
	v_mov_b32 v142, 0
	v_mov_b32 v143, 0
	v_mov_b32 v144, 0
	v_mov_b32 v145, 0
	v_mov_b32 v138, 0
	v_mov_b32 v139, 0
	v_mov_b32 v140, 0
	v_mov_b32 v141, 0
	v_mov_b32 v130, 0
	v_mov_b32 v131, 0
	v_mov_b32 v132, 0
	v_mov_b32 v133, 0
	v_mov_b32 v126, 0
	v_mov_b32 v127, 0
	v_mov_b32 v128, 0
	v_mov_b32 v129, 0
	v_mov_b32 v118, 0
	v_mov_b32 v119, 0
	v_mov_b32 v120, 0
	v_mov_b32 v121, 0
	v_mov_b32 v114, 0
	v_mov_b32 v115, 0
	v_mov_b32 v116, 0
	v_mov_b32 v117, 0
	v_mov_b32 v106, 0
	v_mov_b32 v107, 0
	v_mov_b32 v108, 0
	v_mov_b32 v109, 0
	v_mov_b32 v102, 0
	v_mov_b32 v103, 0
	v_mov_b32 v104, 0
	v_mov_b32 v105, 0
	v_mov_b32 v94, 0
	v_mov_b32 v95, 0
	v_mov_b32 v96, 0
	v_mov_b32 v97, 0
	v_mov_b32 v86, 0
	v_mov_b32 v87, 0
	v_mov_b32 v88, 0
	v_mov_b32 v89, 0
	v_mov_b32 v78, 0
	v_mov_b32 v79, 0
	v_mov_b32 v80, 0
	v_mov_b32 v81, 0
	s_waitcnt vmcnt(0)
	s_barrier
	s_branch .LBB0_185

.LBB0_184:
	v_add_f32_e32 v20, v189, v190
	v_fmac_f32_e32 v20, v187, v188
	v_add_f32_e32 v187, v18, v19
	v_fmac_f32_e32 v187, v20, v193
	s_add_i32 s89, s89, 2
	s_cmp_lg_u32 0, -1
	s_cselect_b32 s36, 0, 0
	s_add_i32 s36, s36, 0x18000
	s_waitcnt lgkmcnt(0)
	v_add_u32_e32 v220, s36, v255
	v_xor_b32_e32 v221, 0x110, v220
	ds_read_b64_tr_b16 v[18:19], v220 offset:0
	ds_read_b64_tr_b16 v[20:21], v221 offset:0
	v_xor_b32_e32 v222, 32, v220
	ds_read_b64_tr_b16 v[22:23], v222 offset:0
	v_xor_b32_e32 v226, 32, v221
	ds_read_b64_tr_b16 v[24:25], v226 offset:0
	ds_read_b64_tr_b16 v[26:27], v220 offset:0x200
	ds_read_b64_tr_b16 v[28:29], v221 offset:0x200
	s_waitcnt lgkmcnt(4)
	v_permlane16_swap_b32_e32 v10, v14
	v_permlane16_swap_b32_e32 v11, v15
	v_permlane16_swap_b32_e32 v12, v16
	v_permlane16_swap_b32_e32 v13, v17
	v_permlane16_swap_b32_e32 v2, v6
	v_permlane16_swap_b32_e32 v3, v7
	v_permlane16_swap_b32_e32 v4, v8
	v_permlane16_swap_b32_e32 v5, v9
	v_mfma_f32_16x16x32_bf16 v[30:33], v[10:13], v[18:21], v[74:77]
	v_mfma_f32_16x16x32_bf16 v[18:21], v[14:17], v[18:21], v[130:133]
	ds_read_b64_tr_b16 v[74:75], v222 offset:0x200
	ds_read_b64_tr_b16 v[76:77], v226 offset:0x200
	s_waitcnt lgkmcnt(4)
	v_mfma_f32_16x16x32_bf16 v[78:81], v[10:13], v[22:25], v[78:81]
	v_mfma_f32_16x16x32_bf16 v[22:25], v[14:17], v[22:25], v[134:137]
	ds_read_b64_tr_b16 v[130:131], v220 offset:0x400
	ds_read_b64_tr_b16 v[132:133], v221 offset:0x400
	s_waitcnt lgkmcnt(4)
	v_mfma_f32_16x16x32_bf16 v[82:85], v[10:13], v[26:29], v[82:85]
	v_mfma_f32_16x16x32_bf16 v[26:29], v[14:17], v[26:29], v[138:141]
	ds_read_b64_tr_b16 v[134:135], v222 offset:0x400
	ds_read_b64_tr_b16 v[136:137], v226 offset:0x400
	s_waitcnt lgkmcnt(4)
	v_mfma_f32_16x16x32_bf16 v[86:89], v[10:13], v[74:77], v[86:89]
	v_mfma_f32_16x16x32_bf16 v[74:77], v[14:17], v[74:77], v[142:145]
	ds_read_b64_tr_b16 v[138:139], v220 offset:0x600
	ds_read_b64_tr_b16 v[140:141], v221 offset:0x600
	s_waitcnt lgkmcnt(4)
	v_mfma_f32_16x16x32_bf16 v[90:93], v[10:13], v[130:133], v[90:93]
	v_mfma_f32_16x16x32_bf16 v[130:133], v[14:17], v[130:133], v[146:149]
	ds_read_b64_tr_b16 v[142:143], v222 offset:0x600
	ds_read_b64_tr_b16 v[144:145], v226 offset:0x600
	s_waitcnt lgkmcnt(4)
	v_mfma_f32_16x16x32_bf16 v[94:97], v[10:13], v[134:137], v[94:97]
	v_mfma_f32_16x16x32_bf16 v[134:137], v[14:17], v[134:137], v[150:153]
	ds_read_b64_tr_b16 v[146:147], v220 offset:0x2000
	ds_read_b64_tr_b16 v[148:149], v221 offset:0x2000
	s_waitcnt lgkmcnt(4)
	v_mfma_f32_16x16x32_bf16 v[98:101], v[10:13], v[138:141], v[98:101]
	v_mfma_f32_16x16x32_bf16 v[138:141], v[14:17], v[138:141], v[154:157]
	ds_read_b64_tr_b16 v[150:151], v222 offset:0x2000
	ds_read_b64_tr_b16 v[152:153], v226 offset:0x2000
	s_waitcnt lgkmcnt(4)
	v_mfma_f32_16x16x32_bf16 v[102:105], v[10:13], v[142:145], v[102:105]
	v_mfma_f32_16x16x32_bf16 v[158:161], v[14:17], v[142:145], v[158:161]
	ds_read_b64_tr_b16 v[142:143], v220 offset:0x2200
	ds_read_b64_tr_b16 v[144:145], v221 offset:0x2200
	s_waitcnt lgkmcnt(4)
	v_mfma_f32_16x16x32_bf16 v[106:109], v[10:13], v[146:149], v[106:109]
	v_mfma_f32_16x16x32_bf16 v[146:149], v[14:17], v[146:149], v[162:165]
	ds_read_b64_tr_b16 v[154:155], v222 offset:0x2200
	ds_read_b64_tr_b16 v[156:157], v226 offset:0x2200
	s_waitcnt lgkmcnt(4)
	v_mfma_f32_16x16x32_bf16 v[188:191], v[10:13], v[150:153], v[110:113]
	v_mfma_f32_16x16x32_bf16 v[192:195], v[14:17], v[150:153], v[166:169]
	ds_read_b64_tr_b16 v[110:111], v220 offset:0x2400
	ds_read_b64_tr_b16 v[112:113], v221 offset:0x2400
	s_waitcnt lgkmcnt(4)
	v_mfma_f32_16x16x32_bf16 v[114:117], v[10:13], v[142:145], v[114:117]
	v_mfma_f32_16x16x32_bf16 v[170:173], v[14:17], v[142:145], v[170:173]
	ds_read_b64_tr_b16 v[142:143], v222 offset:0x2400
	ds_read_b64_tr_b16 v[144:145], v226 offset:0x2400
	s_waitcnt lgkmcnt(4)
	v_mfma_f32_16x16x32_bf16 v[174:177], v[14:17], v[154:157], v[174:177]
	v_mfma_f32_16x16x32_bf16 v[196:199], v[10:13], v[154:157], v[118:121]
	ds_read_b64_tr_b16 v[118:119], v220 offset:0x2600
	ds_read_b64_tr_b16 v[120:121], v221 offset:0x2600
	s_waitcnt lgkmcnt(4)
	v_mfma_f32_16x16x32_bf16 v[200:203], v[10:13], v[110:113], v[122:125]
	v_mfma_f32_16x16x32_bf16 v[204:207], v[14:17], v[110:113], v[178:181]
	ds_read_b64_tr_b16 v[110:111], v222 offset:0x2600
	ds_read_b64_tr_b16 v[112:113], v226 offset:0x2600
	s_waitcnt lgkmcnt(4)
	v_mfma_f32_16x16x32_bf16 v[182:185], v[14:17], v[142:145], v[182:185]
	v_mfma_f32_16x16x32_bf16 v[208:211], v[10:13], v[142:145], v[126:129]
	ds_read_b64_tr_b16 v[122:123], v220 offset:0x4000
	ds_read_b64_tr_b16 v[124:125], v221 offset:0x4000
	s_waitcnt lgkmcnt(4)
	v_mfma_f32_16x16x32_bf16 v[212:215], v[10:13], v[118:121], v[66:69]
	v_mfma_f32_16x16x32_bf16 v[216:219], v[14:17], v[118:121], v[70:73]
	ds_read_b64_tr_b16 v[66:67], v222 offset:0x4000
	ds_read_b64_tr_b16 v[68:69], v226 offset:0x4000
	s_waitcnt lgkmcnt(4)
	v_mfma_f32_16x16x32_bf16 v[10:13], v[10:13], v[110:113], v[58:61]
	v_mfma_f32_16x16x32_bf16 v[14:17], v[14:17], v[110:113], v[62:65]
	ds_read_b64_tr_b16 v[70:71], v220 offset:0x4200
	ds_read_b64_tr_b16 v[72:73], v221 offset:0x4200
	s_waitcnt lgkmcnt(4)
	v_mfma_f32_16x16x32_bf16 v[58:61], v[2:5], v[122:125], v[30:33]
	v_mfma_f32_16x16x32_bf16 v[178:181], v[6:9], v[122:125], v[18:21]
	ds_read_b64_tr_b16 v[18:19], v222 offset:0x4200
	ds_read_b64_tr_b16 v[20:21], v226 offset:0x4200
	s_waitcnt lgkmcnt(4)
	v_mfma_f32_16x16x32_bf16 v[62:65], v[2:5], v[66:69], v[78:81]
	v_mfma_f32_16x16x32_bf16 v[166:169], v[6:9], v[66:69], v[22:25]
	ds_read_b64_tr_b16 v[22:23], v220 offset:0x4400
	ds_read_b64_tr_b16 v[24:25], v221 offset:0x4400
	s_waitcnt lgkmcnt(4)
	v_mfma_f32_16x16x32_bf16 v[66:69], v[2:5], v[70:73], v[82:85]
	v_mfma_f32_16x16x32_bf16 v[162:165], v[6:9], v[70:73], v[26:29]
	ds_read_b64_tr_b16 v[26:27], v222 offset:0x4400
	ds_read_b64_tr_b16 v[28:29], v226 offset:0x4400
	s_waitcnt lgkmcnt(4)
	v_mfma_f32_16x16x32_bf16 v[70:73], v[2:5], v[18:21], v[86:89]
	v_mfma_f32_16x16x32_bf16 v[154:157], v[6:9], v[18:21], v[74:77]
	ds_read_b64_tr_b16 v[18:19], v220 offset:0x4600
	ds_read_b64_tr_b16 v[20:21], v221 offset:0x4600
	s_waitcnt lgkmcnt(4)
	v_mfma_f32_16x16x32_bf16 v[74:77], v[2:5], v[22:25], v[90:93]
	v_mfma_f32_16x16x32_bf16 v[150:153], v[6:9], v[22:25], v[130:133]
	ds_read_b64_tr_b16 v[22:23], v222 offset:0x4600
	ds_read_b64_tr_b16 v[24:25], v226 offset:0x4600
	s_waitcnt lgkmcnt(4)
	v_mfma_f32_16x16x32_bf16 v[82:85], v[2:5], v[26:29], v[94:97]
	v_mfma_f32_16x16x32_bf16 v[142:145], v[6:9], v[26:29], v[134:137]
	ds_read_b64_tr_b16 v[26:27], v220 offset:0x6000
	ds_read_b64_tr_b16 v[28:29], v221 offset:0x6000
	s_waitcnt lgkmcnt(4)
	v_mfma_f32_16x16x32_bf16 v[90:93], v[2:5], v[18:21], v[98:101]
	v_mfma_f32_16x16x32_bf16 v[138:141], v[6:9], v[18:21], v[138:141]
	ds_read_b64_tr_b16 v[18:19], v222 offset:0x6000
	ds_read_b64_tr_b16 v[20:21], v226 offset:0x6000
	s_waitcnt lgkmcnt(4)
	v_mfma_f32_16x16x32_bf16 v[98:101], v[2:5], v[22:25], v[102:105]
	v_mfma_f32_16x16x32_bf16 v[130:133], v[6:9], v[22:25], v[158:161]
	ds_read_b64_tr_b16 v[22:23], v220 offset:0x6200
	ds_read_b64_tr_b16 v[24:25], v221 offset:0x6200
	s_waitcnt lgkmcnt(4)
	v_mfma_f32_16x16x32_bf16 v[110:113], v[2:5], v[26:29], v[106:109]
	v_mfma_f32_16x16x32_bf16 v[126:129], v[6:9], v[26:29], v[146:149]
	ds_read_b64_tr_b16 v[26:27], v222 offset:0x6200
	ds_read_b64_tr_b16 v[28:29], v226 offset:0x6200
	s_waitcnt lgkmcnt(4)
	v_mfma_f32_16x16x32_bf16 v[122:125], v[2:5], v[18:21], v[188:191]
	v_mfma_f32_16x16x32_bf16 v[118:121], v[6:9], v[18:21], v[192:195]
	ds_read_b64_tr_b16 v[18:19], v220 offset:0x6400
	ds_read_b64_tr_b16 v[20:21], v221 offset:0x6400
	s_waitcnt lgkmcnt(4)
	v_mfma_f32_16x16x32_bf16 v[134:137], v[2:5], v[22:25], v[114:117]
	v_mfma_f32_16x16x32_bf16 v[114:117], v[6:9], v[22:25], v[170:173]
	ds_read_b64_tr_b16 v[22:23], v222 offset:0x6400
	ds_read_b64_tr_b16 v[24:25], v226 offset:0x6400
	s_waitcnt lgkmcnt(4)
	v_mfma_f32_16x16x32_bf16 v[146:149], v[2:5], v[26:29], v[196:199]
	v_mfma_f32_16x16x32_bf16 v[106:109], v[6:9], v[26:29], v[174:177]
	ds_read_b64_tr_b16 v[26:27], v220 offset:0x6600
	ds_read_b64_tr_b16 v[28:29], v221 offset:0x6600
	s_waitcnt lgkmcnt(4)
	v_mfma_f32_16x16x32_bf16 v[158:161], v[2:5], v[18:21], v[200:203]
	v_mfma_f32_16x16x32_bf16 v[102:105], v[6:9], v[18:21], v[204:207]
	ds_read_b64_tr_b16 v[18:19], v222 offset:0x6600
	ds_read_b64_tr_b16 v[20:21], v226 offset:0x6600
	s_waitcnt lgkmcnt(4)
	v_mfma_f32_16x16x32_bf16 v[174:177], v[2:5], v[22:25], v[208:211]
	v_mfma_f32_16x16x32_bf16 v[94:97], v[6:9], v[22:25], v[182:185]
	s_waitcnt lgkmcnt(2)
	v_mfma_f32_16x16x32_bf16 v[182:185], v[2:5], v[26:29], v[212:215]
	v_mfma_f32_16x16x32_bf16 v[86:89], v[6:9], v[26:29], v[216:219]
	s_waitcnt lgkmcnt(0)
	s_waitcnt vmcnt(0)
	s_barrier
	v_mfma_f32_16x16x32_bf16 v[170:173], v[2:5], v[18:21], v[10:13]
	v_mfma_f32_16x16x32_bf16 v[78:81], v[6:9], v[18:21], v[14:17]
	s_addk_i32 s86, 0xff80
	s_addk_i32 s79, 0x80
	s_add_u32 s8, s8, 0x500000
	s_addc_u32 s9, s9, 0
	s_and_b64 vcc, exec, s[34:35]
	s_cbranch_vccnz .LBB0_202
.LBB0_185:
	v_mbcnt_lo_u32_b32 v192, -1, 0
	v_mbcnt_hi_u32_b32 v192, -1, v192
	s_add_i32 s35, 0, 0x10000
	s_add_i32 s37, s35, s61
	s_add_i32 s92, s37, 0x4000
	s_add_i32 s35, s35, s65
	s_add_i32 s93, s35, 0x4000
	s_add_u32 s98, s8, s14
	s_addc_u32 s99, s9, s15
	s_add_u32 s100, s8, s28
	s_addc_u32 s101, s9, s29
	s_add_i32 s36, s68, s79
	s_add_i32 s90, s36, 64
	s_add_i32 s34, s79, 63
	s_mul_hi_i32 s91, s90, 0xa000
	s_mul_i32 s90, s90, 0xa000
	s_add_u32 s90, s82, s90
	s_addc_u32 s91, s83, s91
	s_add_i32 s94, s47, s70
	s_add_i32 s95, s94, 0x380
	s_add_i32 s96, s47, s74
	s_add_i32 s97, s47, s77
	s_addk_i32 s97, 0xff80
	v_ashrrev_i32_e32 v188, 5, v192
	v_and_b32_e32 v193, 31, v192
	v_lshlrev_b32_e32 v189, 4, v192
	v_lshlrev_b32_e32 v191, 4, v188
	v_lshlrev_b32_e32 v190, 8, v193
	v_bitop3_b32 v2, v189, v191, s48 bitop3:0x6c
	v_add3_u32 v6, s84, v2, v190
	v_add_u32_e32 v7, 32, v191
	v_bitop3_b32 v7, v7, v189, s48 bitop3:0x78
	v_add3_u32 v250, s84, v7, v190
	v_add_u32_e32 v7, 64, v191
	v_bitop3_b32 v7, v7, v189, s48 bitop3:0x78
	v_add3_u32 v222, s84, v7, v190
	v_add_u32_e32 v7, 0x60, v191
	v_bitop3_b32 v7, v7, v189, s48 bitop3:0x78
	v_add3_u32 v190, s84, v7, v190
	v_add_u32_e32 v189, s81, v189
	ds_read_b128 v[2:5], v6
	ds_read_b128 v[194:197], v6 offset:8192
	ds_read_b128 v[198:201], v250
	ds_read_b128 v[202:205], v250 offset:8192
	ds_read_b128 v[206:209], v222
	ds_read_b128 v[210:213], v222 offset:8192
	ds_read_b128 v[214:217], v190
	ds_read_b128 v[218:221], v190 offset:8192
	ds_read_b128 v[226:229], v6 offset:128
	ds_read_b128 v[230:233], v6 offset:8320
	s_waitcnt lgkmcnt(9)
	s_mov_b32 m0, s37
	v_mfma_f32_32x32x16_bf16 v[18:33], v[2:5], v[34:37], 0
	global_load_lds_dwordx4 v251, s[98:99]
	s_waitcnt lgkmcnt(8)
	s_mov_b32 m0, s92
	v_mfma_f32_32x32x16_bf16 v[2:17], v[194:197], v[34:37], 0
	global_load_lds_dwordx4 v251, s[100:101]
	ds_read_b128 v[194:197], v250 offset:128
	s_waitcnt lgkmcnt(8)
	s_mov_b32 m0, s35
	v_mfma_f32_32x32x16_bf16 v[18:33], v[198:201], v[38:41], v[18:33]
	global_load_lds_dwordx4 v252, s[98:99]
	ds_read_b128 v[198:201], v250 offset:8320
	s_waitcnt lgkmcnt(8)
	s_mov_b32 m0, s93
	v_mfma_f32_32x32x16_bf16 v[2:17], v[202:205], v[38:41], v[2:17]
	global_load_lds_dwordx4 v252, s[100:101]
	ds_read_b128 v[202:205], v222 offset:128
	s_waitcnt lgkmcnt(8)
	s_mov_b32 m0, s94
	v_mfma_f32_32x32x16_bf16 v[18:33], v[206:209], v[42:45], v[18:33]
	global_load_lds_dwordx4 v253, s[90:91]
	ds_read_b128 v[206:209], v222 offset:8320
	s_waitcnt lgkmcnt(8)
	s_mov_b32 m0, s95
	v_mfma_f32_32x32x16_bf16 v[2:17], v[210:213], v[42:45], v[2:17]
	global_load_lds_dwordx4 v253, s[90:91] offset:128
	ds_read_b128 v[210:213], v190 offset:128
	s_waitcnt lgkmcnt(8)
	s_mov_b32 m0, s96
	v_mfma_f32_32x32x16_bf16 v[18:33], v[214:217], v[46:49], v[18:33]
	global_load_lds_dwordx4 v254, s[90:91]
	ds_read_b128 v[214:217], v190 offset:8320
	s_waitcnt lgkmcnt(8)
	s_mov_b32 m0, s97
	v_mfma_f32_32x32x16_bf16 v[2:17], v[218:221], v[46:49], v[2:17]
	global_load_lds_dwordx4 v254, s[90:91] offset:128
	ds_read_b128 v[218:221], v189
	s_waitcnt lgkmcnt(8)
	v_mfma_f32_32x32x16_bf16 v[18:33], v[226:229], v[50:53], v[18:33]
	ds_read_b128 v[226:229], v189 offset:1024
	s_waitcnt lgkmcnt(8)
	v_mfma_f32_32x32x16_bf16 v[2:17], v[230:233], v[50:53], v[2:17]
	s_waitcnt lgkmcnt(7)
	v_mfma_f32_32x32x16_bf16 v[18:33], v[194:197], v[54:57], v[18:33]
	s_waitcnt lgkmcnt(6)
	v_mfma_f32_32x32x16_bf16 v[2:17], v[198:201], v[54:57], v[2:17]
	s_waitcnt lgkmcnt(1)
	v_mfma_f32_32x32x16_bf16 v[18:33], v[202:205], v[218:221], v[18:33]
	v_mfma_f32_32x32x16_bf16 v[2:17], v[206:209], v[218:221], v[2:17]
	s_waitcnt lgkmcnt(0)
	v_mfma_f32_32x32x16_bf16 v[18:33], v[210:213], v[226:229], v[18:33]
	s_cmp_le_u32 s34, s59
	v_mfma_f32_32x32x16_bf16 v[2:17], v[214:217], v[226:229], v[2:17]
	s_cbranch_scc1 .LBB0_187
	v_lshlrev_b32_e32 v188, 2, v188
	v_sub_u32_e32 v188, v193, v188
	v_add_u32_e32 v188, s86, v188
	v_add_u32_e32 v189, 0x80000001, v188
	v_cmp_gt_u32_e32 vcc, s46, v189
	s_nop 4
	v_cndmask_b32_e32 v18, v225, v18, vcc
	v_cmp_lt_i32_e32 vcc, 31, v189
	s_nop 1
	v_cndmask_b32_e32 v2, v225, v2, vcc
	v_cmp_lt_i32_e32 vcc, 0, v189
	v_subrev_u32_e32 v189, 31, v188
	s_nop 0
	v_cndmask_b32_e32 v19, v225, v19, vcc
	v_cmp_lt_u32_e32 vcc, s49, v189
	v_subrev_u32_e32 v189, 32, v188
	s_nop 0
	v_cndmask_b32_e32 v3, v225, v3, vcc
	v_cmp_lt_u32_e32 vcc, s49, v188
	s_nop 1
	v_cndmask_b32_e32 v20, v225, v20, vcc
	v_cmp_lt_u32_e32 vcc, s49, v189
	v_add_u32_e32 v189, -1, v188
	s_nop 0
	v_cndmask_b32_e32 v4, v225, v4, vcc
	v_cmp_lt_u32_e32 vcc, s49, v189
	v_subrev_u32_e32 v189, 33, v188
	s_nop 0
	v_cndmask_b32_e32 v21, v225, v21, vcc
	v_cmp_lt_u32_e32 vcc, s49, v189
	v_add_u32_e32 v189, -6, v188
	s_nop 0
	v_cndmask_b32_e32 v5, v225, v5, vcc
	v_cmp_lt_u32_e32 vcc, s49, v189
	v_subrev_u32_e32 v189, 38, v188
	s_nop 0
	v_cndmask_b32_e32 v22, v225, v22, vcc
	v_cmp_lt_u32_e32 vcc, s49, v189
	v_add_u32_e32 v189, -7, v188
	s_nop 0
	v_cndmask_b32_e32 v6, v225, v6, vcc
	v_cmp_lt_u32_e32 vcc, s49, v189
	v_subrev_u32_e32 v189, 39, v188
	s_nop 0
	v_cndmask_b32_e32 v23, v225, v23, vcc
	v_cmp_lt_u32_e32 vcc, s49, v189
	v_add_u32_e32 v189, -8, v188
	s_nop 0
	v_cndmask_b32_e32 v7, v225, v7, vcc
	v_cmp_lt_u32_e32 vcc, s49, v189
	v_subrev_u32_e32 v189, 40, v188
	s_nop 0
	v_cndmask_b32_e32 v24, v225, v24, vcc
	v_cmp_lt_u32_e32 vcc, s49, v189
	v_add_u32_e32 v189, -9, v188
	s_nop 0
	v_cndmask_b32_e32 v8, v225, v8, vcc
	v_cmp_lt_u32_e32 vcc, s49, v189
	v_subrev_u32_e32 v189, 41, v188
	s_nop 0
	v_cndmask_b32_e32 v25, v225, v25, vcc
	v_cmp_lt_u32_e32 vcc, s49, v189
	v_add_u32_e32 v189, -14, v188
	s_nop 0
	v_cndmask_b32_e32 v9, v225, v9, vcc
	v_cmp_lt_u32_e32 vcc, s49, v189
	v_subrev_u32_e32 v189, 46, v188
	s_nop 0
	v_cndmask_b32_e32 v26, v225, v26, vcc
	v_cmp_lt_u32_e32 vcc, s49, v189
	v_add_u32_e32 v189, -15, v188
	s_nop 0
	v_cndmask_b32_e32 v10, v225, v10, vcc
	v_cmp_lt_u32_e32 vcc, s49, v189
	v_subrev_u32_e32 v189, 47, v188
	s_nop 0
	v_cndmask_b32_e32 v27, v225, v27, vcc
	v_cmp_lt_u32_e32 vcc, s49, v189
	v_add_u32_e32 v189, -16, v188
	s_nop 0
	v_cndmask_b32_e32 v11, v225, v11, vcc
	v_cmp_lt_u32_e32 vcc, s49, v189
	v_subrev_u32_e32 v189, 48, v188
	s_nop 0
	v_cndmask_b32_e32 v28, v225, v28, vcc
	v_cmp_lt_u32_e32 vcc, s49, v189
	v_subrev_u32_e32 v189, 17, v188
	s_nop 0
	v_cndmask_b32_e32 v12, v225, v12, vcc
	v_cmp_lt_u32_e32 vcc, s49, v189
	v_subrev_u32_e32 v189, 49, v188
	s_nop 0
	v_cndmask_b32_e32 v29, v225, v29, vcc
	v_cmp_lt_u32_e32 vcc, s49, v189
	v_subrev_u32_e32 v189, 22, v188
	s_nop 0
	v_cndmask_b32_e32 v13, v225, v13, vcc
	v_cmp_lt_u32_e32 vcc, s49, v189
	v_subrev_u32_e32 v189, 54, v188
	s_nop 0
	v_cndmask_b32_e32 v30, v225, v30, vcc
	v_cmp_lt_u32_e32 vcc, s49, v189
	v_subrev_u32_e32 v189, 23, v188
	s_nop 0
	v_cndmask_b32_e32 v14, v225, v14, vcc
	v_cmp_lt_u32_e32 vcc, s49, v189
	v_subrev_u32_e32 v189, 55, v188
	s_nop 0
	v_cndmask_b32_e32 v31, v225, v31, vcc
	v_cmp_lt_u32_e32 vcc, s49, v189
	v_subrev_u32_e32 v189, 24, v188
	s_nop 0
	v_cndmask_b32_e32 v15, v225, v15, vcc
	v_cmp_lt_u32_e32 vcc, s49, v189
	v_subrev_u32_e32 v189, 56, v188
	s_nop 0
	v_cndmask_b32_e32 v32, v225, v32, vcc
	v_cmp_lt_u32_e32 vcc, s49, v189
	v_subrev_u32_e32 v189, 25, v188
	v_subrev_u32_e32 v188, 57, v188
	v_cndmask_b32_e32 v16, v225, v16, vcc
	v_cmp_lt_u32_e32 vcc, s49, v189
	s_nop 1
	v_cndmask_b32_e32 v33, v225, v33, vcc
	v_cmp_lt_u32_e32 vcc, s49, v188
	s_nop 1
	v_cndmask_b32_e32 v17, v225, v17, vcc

.LBB0_192:
	s_cmp_lg_u32 0, -1
	s_cselect_b32 s34, 0, 0
	s_add_i32 s34, s34, 0x8000
	s_waitcnt lgkmcnt(0)
	v_add_u32_e32 v220, s34, v255
	v_xor_b32_e32 v221, 0x110, v220
	ds_read_b64_tr_b16 v[18:19], v220 offset:0
	ds_read_b64_tr_b16 v[20:21], v221 offset:0
	v_xor_b32_e32 v222, 32, v220
	ds_read_b64_tr_b16 v[22:23], v222 offset:0
	v_xor_b32_e32 v250, 32, v221
	ds_read_b64_tr_b16 v[24:25], v250 offset:0
	ds_read_b64_tr_b16 v[26:27], v220 offset:0x200
	ds_read_b64_tr_b16 v[28:29], v221 offset:0x200
	s_waitcnt lgkmcnt(4)
	v_permlane16_swap_b32_e32 v10, v14
	v_permlane16_swap_b32_e32 v11, v15
	v_permlane16_swap_b32_e32 v12, v16
	v_permlane16_swap_b32_e32 v13, v17
	v_permlane16_swap_b32_e32 v2, v6
	v_permlane16_swap_b32_e32 v3, v7
	v_permlane16_swap_b32_e32 v4, v8
	v_permlane16_swap_b32_e32 v5, v9
	v_mfma_f32_16x16x32_bf16 v[30:33], v[10:13], v[18:21], v[58:61]
	v_mfma_f32_16x16x32_bf16 v[18:21], v[14:17], v[18:21], v[178:181]
	ds_read_b64_tr_b16 v[58:59], v222 offset:0x200
	ds_read_b64_tr_b16 v[60:61], v250 offset:0x200
	s_waitcnt lgkmcnt(4)
	v_mfma_f32_16x16x32_bf16 v[62:65], v[10:13], v[22:25], v[62:65]
	v_mfma_f32_16x16x32_bf16 v[22:25], v[14:17], v[22:25], v[166:169]
	ds_read_b64_tr_b16 v[166:167], v220 offset:0x400
	ds_read_b64_tr_b16 v[168:169], v221 offset:0x400
	s_waitcnt lgkmcnt(4)
	v_mfma_f32_16x16x32_bf16 v[66:69], v[10:13], v[26:29], v[66:69]
	v_mfma_f32_16x16x32_bf16 v[26:29], v[14:17], v[26:29], v[162:165]
	ds_read_b64_tr_b16 v[162:163], v222 offset:0x400
	ds_read_b64_tr_b16 v[164:165], v250 offset:0x400
	s_waitcnt lgkmcnt(4)
	v_mfma_f32_16x16x32_bf16 v[70:73], v[10:13], v[58:61], v[70:73]
	v_mfma_f32_16x16x32_bf16 v[58:61], v[14:17], v[58:61], v[154:157]
	ds_read_b64_tr_b16 v[154:155], v220 offset:0x600
	ds_read_b64_tr_b16 v[156:157], v221 offset:0x600
	s_waitcnt lgkmcnt(4)
	v_mfma_f32_16x16x32_bf16 v[178:181], v[10:13], v[166:169], v[74:77]
	v_mfma_f32_16x16x32_bf16 v[150:153], v[14:17], v[166:169], v[150:153]
	ds_read_b64_tr_b16 v[74:75], v222 offset:0x600
	ds_read_b64_tr_b16 v[76:77], v250 offset:0x600
	s_waitcnt lgkmcnt(4)
	v_mfma_f32_16x16x32_bf16 v[166:169], v[10:13], v[162:165], v[82:85]
	v_mfma_f32_16x16x32_bf16 v[162:165], v[14:17], v[162:165], v[142:145]
	ds_read_b64_tr_b16 v[82:83], v220 offset:0x2000
	ds_read_b64_tr_b16 v[84:85], v221 offset:0x2000
	s_waitcnt lgkmcnt(4)
	v_mfma_f32_16x16x32_bf16 v[192:195], v[10:13], v[154:157], v[90:93]
	v_mfma_f32_16x16x32_bf16 v[154:157], v[14:17], v[154:157], v[138:141]
	ds_read_b64_tr_b16 v[90:91], v222 offset:0x2000
	ds_read_b64_tr_b16 v[92:93], v250 offset:0x2000
	s_waitcnt lgkmcnt(4)
	v_mfma_f32_16x16x32_bf16 v[196:199], v[10:13], v[74:77], v[98:101]
	v_mfma_f32_16x16x32_bf16 v[200:203], v[14:17], v[74:77], v[130:133]
	ds_read_b64_tr_b16 v[74:75], v220 offset:0x2200
	ds_read_b64_tr_b16 v[76:77], v221 offset:0x2200
	s_waitcnt lgkmcnt(4)
	v_mfma_f32_16x16x32_bf16 v[110:113], v[10:13], v[82:85], v[110:113]
	v_mfma_f32_16x16x32_bf16 v[126:129], v[14:17], v[82:85], v[126:129]
	ds_read_b64_tr_b16 v[82:83], v222 offset:0x2200
	ds_read_b64_tr_b16 v[84:85], v250 offset:0x2200
	s_waitcnt lgkmcnt(4)
	v_mfma_f32_16x16x32_bf16 v[122:125], v[10:13], v[90:93], v[122:125]
	v_mfma_f32_16x16x32_bf16 v[118:121], v[14:17], v[90:93], v[118:121]
	ds_read_b64_tr_b16 v[90:91], v220 offset:0x2400
	ds_read_b64_tr_b16 v[92:93], v221 offset:0x2400
	s_waitcnt lgkmcnt(4)
	v_mfma_f32_16x16x32_bf16 v[204:207], v[10:13], v[74:77], v[134:137]
	v_mfma_f32_16x16x32_bf16 v[208:211], v[14:17], v[74:77], v[114:117]
	ds_read_b64_tr_b16 v[74:75], v222 offset:0x2400
	ds_read_b64_tr_b16 v[76:77], v250 offset:0x2400
	s_waitcnt lgkmcnt(4)
	v_mfma_f32_16x16x32_bf16 v[212:215], v[10:13], v[82:85], v[146:149]
	v_mfma_f32_16x16x32_bf16 v[216:219], v[14:17], v[82:85], v[106:109]
	ds_read_b64_tr_b16 v[82:83], v220 offset:0x2600
	ds_read_b64_tr_b16 v[84:85], v221 offset:0x2600
	s_waitcnt lgkmcnt(4)
	v_mfma_f32_16x16x32_bf16 v[226:229], v[10:13], v[90:93], v[158:161]
	v_mfma_f32_16x16x32_bf16 v[230:233], v[14:17], v[90:93], v[102:105]
	ds_read_b64_tr_b16 v[90:91], v222 offset:0x2600
	ds_read_b64_tr_b16 v[92:93], v250 offset:0x2600
	s_waitcnt lgkmcnt(4)
	v_mfma_f32_16x16x32_bf16 v[234:237], v[10:13], v[74:77], v[174:177]
	v_mfma_f32_16x16x32_bf16 v[238:241], v[14:17], v[74:77], v[94:97]
	ds_read_b64_tr_b16 v[94:95], v220 offset:0x4000
	ds_read_b64_tr_b16 v[96:97], v221 offset:0x4000
	s_waitcnt lgkmcnt(4)
	v_mfma_f32_16x16x32_bf16 v[242:245], v[10:13], v[82:85], v[182:185]
	v_mfma_f32_16x16x32_bf16 v[246:249], v[14:17], v[82:85], v[86:89]
	ds_read_b64_tr_b16 v[82:83], v222 offset:0x4000
	ds_read_b64_tr_b16 v[84:85], v250 offset:0x4000
	s_waitcnt lgkmcnt(4)
	v_mfma_f32_16x16x32_bf16 v[10:13], v[10:13], v[90:93], v[170:173]
	v_mfma_f32_16x16x32_bf16 v[14:17], v[14:17], v[90:93], v[78:81]
	ds_read_b64_tr_b16 v[86:87], v220 offset:0x4200
	ds_read_b64_tr_b16 v[88:89], v221 offset:0x4200
	s_waitcnt lgkmcnt(4)
	v_mfma_f32_16x16x32_bf16 v[74:77], v[2:5], v[94:97], v[30:33]
	v_mfma_f32_16x16x32_bf16 v[130:133], v[6:9], v[94:97], v[18:21]
	ds_read_b64_tr_b16 v[18:19], v222 offset:0x4200
	ds_read_b64_tr_b16 v[20:21], v250 offset:0x4200
	s_waitcnt lgkmcnt(4)
	v_mfma_f32_16x16x32_bf16 v[78:81], v[2:5], v[82:85], v[62:65]
	v_mfma_f32_16x16x32_bf16 v[134:137], v[6:9], v[82:85], v[22:25]
	ds_read_b64_tr_b16 v[22:23], v220 offset:0x4400
	ds_read_b64_tr_b16 v[24:25], v221 offset:0x4400
	s_waitcnt lgkmcnt(4)
	v_mfma_f32_16x16x32_bf16 v[82:85], v[2:5], v[86:89], v[66:69]
	v_mfma_f32_16x16x32_bf16 v[138:141], v[6:9], v[86:89], v[26:29]
	ds_read_b64_tr_b16 v[26:27], v222 offset:0x4400
	ds_read_b64_tr_b16 v[28:29], v250 offset:0x4400
	s_waitcnt lgkmcnt(4)
	v_mfma_f32_16x16x32_bf16 v[86:89], v[2:5], v[18:21], v[70:73]
	v_mfma_f32_16x16x32_bf16 v[142:145], v[6:9], v[18:21], v[58:61]
	ds_read_b64_tr_b16 v[18:19], v220 offset:0x4600
	ds_read_b64_tr_b16 v[20:21], v221 offset:0x4600
	s_waitcnt lgkmcnt(4)
	v_mfma_f32_16x16x32_bf16 v[90:93], v[2:5], v[22:25], v[178:181]
	v_mfma_f32_16x16x32_bf16 v[146:149], v[6:9], v[22:25], v[150:153]
	ds_read_b64_tr_b16 v[22:23], v222 offset:0x4600
	ds_read_b64_tr_b16 v[24:25], v250 offset:0x4600
	s_waitcnt lgkmcnt(4)
	v_mfma_f32_16x16x32_bf16 v[94:97], v[2:5], v[26:29], v[166:169]
	v_mfma_f32_16x16x32_bf16 v[150:153], v[6:9], v[26:29], v[162:165]
	ds_read_b64_tr_b16 v[26:27], v220 offset:0x6000
	ds_read_b64_tr_b16 v[28:29], v221 offset:0x6000
	s_waitcnt lgkmcnt(4)
	v_mfma_f32_16x16x32_bf16 v[98:101], v[2:5], v[18:21], v[192:195]
	v_mfma_f32_16x16x32_bf16 v[154:157], v[6:9], v[18:21], v[154:157]
	ds_read_b64_tr_b16 v[18:19], v222 offset:0x6000
	ds_read_b64_tr_b16 v[20:21], v250 offset:0x6000
	s_waitcnt lgkmcnt(4)
	v_mfma_f32_16x16x32_bf16 v[102:105], v[2:5], v[22:25], v[196:199]
	v_mfma_f32_16x16x32_bf16 v[158:161], v[6:9], v[22:25], v[200:203]
	ds_read_b64_tr_b16 v[22:23], v220 offset:0x6200
	ds_read_b64_tr_b16 v[24:25], v221 offset:0x6200
	s_waitcnt lgkmcnt(4)
	v_mfma_f32_16x16x32_bf16 v[106:109], v[2:5], v[26:29], v[110:113]
	v_mfma_f32_16x16x32_bf16 v[162:165], v[6:9], v[26:29], v[126:129]
	ds_read_b64_tr_b16 v[26:27], v222 offset:0x6200
	ds_read_b64_tr_b16 v[28:29], v250 offset:0x6200
	s_waitcnt lgkmcnt(4)
	v_mfma_f32_16x16x32_bf16 v[110:113], v[2:5], v[18:21], v[122:125]
	v_mfma_f32_16x16x32_bf16 v[166:169], v[6:9], v[18:21], v[118:121]
	ds_read_b64_tr_b16 v[18:19], v220 offset:0x6400
	ds_read_b64_tr_b16 v[20:21], v221 offset:0x6400
	s_waitcnt lgkmcnt(4)
	v_mfma_f32_16x16x32_bf16 v[114:117], v[2:5], v[22:25], v[204:207]
	v_mfma_f32_16x16x32_bf16 v[170:173], v[6:9], v[22:25], v[208:211]
	ds_read_b64_tr_b16 v[22:23], v222 offset:0x6400
	ds_read_b64_tr_b16 v[24:25], v250 offset:0x6400
	s_waitcnt lgkmcnt(4)
	v_mfma_f32_16x16x32_bf16 v[118:121], v[2:5], v[26:29], v[212:215]
	v_mfma_f32_16x16x32_bf16 v[174:177], v[6:9], v[26:29], v[216:219]
	ds_read_b64_tr_b16 v[26:27], v220 offset:0x6600
	ds_read_b64_tr_b16 v[28:29], v221 offset:0x6600
	s_waitcnt lgkmcnt(4)
	v_mfma_f32_16x16x32_bf16 v[122:125], v[2:5], v[18:21], v[226:229]
	v_mfma_f32_16x16x32_bf16 v[178:181], v[6:9], v[18:21], v[230:233]
	ds_read_b64_tr_b16 v[18:19], v222 offset:0x6600
	ds_read_b64_tr_b16 v[20:21], v250 offset:0x6600
	s_waitcnt lgkmcnt(4)
	v_mfma_f32_16x16x32_bf16 v[126:129], v[2:5], v[22:25], v[234:237]
	v_mfma_f32_16x16x32_bf16 v[182:185], v[6:9], v[22:25], v[238:241]
	s_waitcnt lgkmcnt(2)
	v_mfma_f32_16x16x32_bf16 v[66:69], v[2:5], v[26:29], v[242:245]
	v_mfma_f32_16x16x32_bf16 v[70:73], v[6:9], v[26:29], v[246:249]
	s_waitcnt lgkmcnt(0)
	s_waitcnt vmcnt(0)
	s_barrier
	v_mfma_f32_16x16x32_bf16 v[58:61], v[2:5], v[18:21], v[10:13]
	v_mfma_f32_16x16x32_bf16 v[62:65], v[6:9], v[18:21], v[14:17]
	s_cmp_ge_u32 s89, s80
	s_cselect_b64 s[34:35], -1, 0
	s_and_b64 vcc, exec, s[34:35]
	v_mbcnt_lo_u32_b32 v192, -1, 0
	v_mbcnt_hi_u32_b32 v192, -1, v192
	s_cbranch_vccnz .LBB0_194
	s_add_u32 s98, s8, s30
	s_addc_u32 s99, s9, s31
	s_addk_i32 s36, 0x80
	s_mul_hi_i32 s37, s36, 0xa000
	s_mul_i32 s36, s36, 0xa000
	s_add_u32 s36, s82, s36
	s_addc_u32 s37, s83, s37
	s_add_i32 s100, s72, 0xffffff80
	s_add_i32 s101, s78, 0xffffff80
	v_ashrrev_i32_e32 v193, 5, v192
	v_and_b32_e32 v194, 31, v192
	v_lshlrev_b32_e32 v195, 4, v192
	v_lshlrev_b32_e32 v221, 4, v193
	v_lshlrev_b32_e32 v220, 8, v194
	v_bitop3_b32 v2, v195, v221, s48 bitop3:0x6c
	v_add3_u32 v6, s85, v2, v220
	v_add_u32_e32 v7, 32, v221
	v_bitop3_b32 v7, v7, v195, s48 bitop3:0x78
	v_add3_u32 v250, s85, v7, v220
	v_add_u32_e32 v7, 64, v221
	v_bitop3_b32 v7, v7, v195, s48 bitop3:0x78
	v_add3_u32 v222, s85, v7, v220
	v_add_u32_e32 v7, 0x60, v221
	v_bitop3_b32 v7, v7, v195, s48 bitop3:0x78
	v_add3_u32 v220, s85, v7, v220
	v_add_u32_e32 v195, s81, v195
	ds_read_b128 v[2:5], v6
	ds_read_b128 v[196:199], v6 offset:8192
	ds_read_b128 v[200:203], v250
	ds_read_b128 v[204:207], v250 offset:8192
	ds_read_b128 v[208:211], v222
	ds_read_b128 v[212:215], v222 offset:8192
	ds_read_b128 v[216:219], v220
	ds_read_b128 v[226:229], v220 offset:8192
	ds_read_b128 v[230:233], v6 offset:128
	ds_read_b128 v[234:237], v6 offset:8320
	s_waitcnt lgkmcnt(9)
	s_mov_b32 m0, s62
	v_mfma_f32_32x32x16_bf16 v[18:33], v[2:5], v[34:37], 0
	global_load_lds_dwordx4 v251, s[98:99]
	s_waitcnt lgkmcnt(8)
	s_mov_b32 m0, s63
	v_mfma_f32_32x32x16_bf16 v[2:17], v[196:199], v[34:37], 0
	global_load_lds_dwordx4 v251, s[8:9]
	ds_read_b128 v[196:199], v250 offset:128
	s_waitcnt lgkmcnt(8)
	s_mov_b32 m0, s66
	v_mfma_f32_32x32x16_bf16 v[18:33], v[200:203], v[38:41], v[18:33]
	global_load_lds_dwordx4 v252, s[98:99]
	ds_read_b128 v[200:203], v250 offset:8320
	s_waitcnt lgkmcnt(8)
	s_mov_b32 m0, s67
	v_mfma_f32_32x32x16_bf16 v[2:17], v[204:207], v[38:41], v[2:17]
	global_load_lds_dwordx4 v252, s[8:9]
	ds_read_b128 v[204:207], v222 offset:128
	s_waitcnt lgkmcnt(8)
	s_mov_b32 m0, s71
	v_mfma_f32_32x32x16_bf16 v[18:33], v[208:211], v[42:45], v[18:33]
	global_load_lds_dwordx4 v253, s[36:37]
	ds_read_b128 v[208:211], v222 offset:8320
	s_waitcnt lgkmcnt(8)
	s_mov_b32 m0, s100
	v_mfma_f32_32x32x16_bf16 v[2:17], v[212:215], v[42:45], v[2:17]
	global_load_lds_dwordx4 v253, s[36:37] offset:128
	ds_read_b128 v[212:215], v220 offset:128
	s_waitcnt lgkmcnt(8)
	s_mov_b32 m0, s75
	v_mfma_f32_32x32x16_bf16 v[18:33], v[216:219], v[46:49], v[18:33]
	global_load_lds_dwordx4 v254, s[36:37]
	ds_read_b128 v[216:219], v220 offset:8320
	s_waitcnt lgkmcnt(8)
	s_mov_b32 m0, s101
	v_mfma_f32_32x32x16_bf16 v[2:17], v[226:229], v[46:49], v[2:17]
	global_load_lds_dwordx4 v254, s[36:37] offset:128
	ds_read_b128 v[226:229], v195
	s_waitcnt lgkmcnt(8)
	v_mfma_f32_32x32x16_bf16 v[18:33], v[230:233], v[50:53], v[18:33]
	ds_read_b128 v[230:233], v195 offset:1024
	s_waitcnt lgkmcnt(8)
	v_mfma_f32_32x32x16_bf16 v[2:17], v[234:237], v[50:53], v[2:17]
	s_waitcnt lgkmcnt(7)
	v_mfma_f32_32x32x16_bf16 v[18:33], v[196:199], v[54:57], v[18:33]
	s_waitcnt lgkmcnt(6)
	v_mfma_f32_32x32x16_bf16 v[2:17], v[200:203], v[54:57], v[2:17]
	s_waitcnt lgkmcnt(1)
	v_mfma_f32_32x32x16_bf16 v[18:33], v[204:207], v[226:229], v[18:33]
	v_mfma_f32_32x32x16_bf16 v[2:17], v[208:211], v[226:229], v[2:17]
	s_waitcnt lgkmcnt(0)
	v_mfma_f32_32x32x16_bf16 v[18:33], v[212:215], v[230:233], v[18:33]
	s_add_i32 s36, s79, 0x7f
	s_cmp_le_u32 s36, s59
	v_mfma_f32_32x32x16_bf16 v[2:17], v[216:219], v[230:233], v[2:17]
	s_branch .Lqk1_join
